# static s_setprio 1 for the younger wave half also over the three phase-6 gla_a item loops (no priority changes existed there), reset before the E-GEMM
# speedup vs baseline: 1.0023x; 1.0023x over previous
; __device__ __forceinline__ void gla_a_item(const Params& P, int item, unsigned char* smem) {
;     float* sGLR = (float*)smem;
;     float* sPart = (float*)(smem + 4096);
;     bf16_t* sKDt = (bf16_t*)(smem + 5120);
;     bf16_t* sVt = (bf16_t*)(smem + 5120 + 9216);
;     const int n = item % 132, d = (item / 132) & 1, h = (item / 264) & 3, b = item / 1056;
;     const int rowbase = n < 4 ? NL + b * 256 + n * 64 : b * 8192 + (n - 4) * 64;
;     const bf16_t* Kb = (const bf16_t*)(P.ws + OFF_K); const bf16_t* V = (const bf16_t*)(P.ws + OFF_V); const bf16_t* GLR = (const bf16_t*)(P.ws + OFF_GLR);
;     const int tid = threadIdx.x & 255, lane = tid & 63, w = tid >> 6, dk = tid & 63, part = tid >> 6;
;     const VRegs vr = load_v_regs(V + (size_t)rowbase * 512 + h * 128, tid);
;     const f32x4 gl4 = load_bf4(GLR + (size_t)(rowbase + (tid >> 2)) * 32 + d * 16 + (tid & 3) * 4);
;     float kk[16];
; #pragma unroll
;     for (int ii = 0; ii < 16; ++ii) kk[ii] = bf2f(Kb[(size_t)(rowbase + part * 16 + ii) * 256 + h * 64 + dk]);
;     const GateW gw = load_gate_w(P, d, h, dk);
;     *(f32x4*)(sGLR + (tid >> 2) * 16 + (tid & 3) * 4) = gl4;
;     store_vt(vr, sVt, tid);
;     __syncthreads();
;     float pre[16];
;     const float tot = gate_prefix(gw, sGLR, 16, d, part, pre);
;     sPart[part * 64 + dk] = tot;
;     __syncthreads();
;     const float t0 = sPart[dk], t1 = sPart[64 + dk], t2 = sPart[128 + dk], t3 = sPart[192 + dk];
;     const float gtot = (t0 + t1) + (t2 + t3);
;     float off;
;     if (d == 0) off = part == 0 ? 0.f : (part == 1 ? t0 : (part == 2 ? t0 + t1 : t0 + t1 + t2));
;     else off = part == 3 ? 0.f : (part == 2 ? t3 : (part == 1 ? t3 + t2 : t3 + t2 + t1));
;     unsigned pk[8];
; #pragma unroll
; __device__ __forceinline__ void phase6(const Params& P, unsigned char* smem) {
;     const int hb = threadIdx.x >> 8;
;     if (gridDim.x == 256) {
;         if (blockIdx.x < 160) { for (int base = blockIdx.x * 2; base < 2240; base += 320) gla_a_item(P, base + hb, smem + hb * HALF_LDS); }
;         else { for (int base = 2240 + ((int)blockIdx.x - 160) * 2; base < 4224; base += 192) gla_a_item(P, base + hb, smem + hb * HALF_LDS); }
;     } else
;     for (int base = blockIdx.x * 2; base < 4224; base += gridDim.x * 2) gla_a_item(P, base + hb, smem + hb * HALF_LDS);
.LBB0_1012:
	s_cmp_lt_i32 s70, 7
	s_cselect_b64 s[0:1], -1, 0
	s_cmp_gt_i32 s71, 6
	s_cselect_b64 s[2:3], -1, 0
	s_and_b64 s[0:1], s[0:1], s[2:3]
	s_andn2_b64 vcc, exec, s[0:1]
	s_cbranch_vccnz .LBB0_1237
	s_waitcnt vmcnt(0)
	v_lshrrev_b32_e32 v46, 8, v168
	s_cmpk_lg_i32 s90, 0x100
	s_mov_b64 s[0:1], -1
	s_cbranch_scc0 .LBB0_1054
	s_lshl_b32 s9, s33, 1
	s_cmpk_gt_i32 s9, 0x107f
	s_cbranch_scc1 .LBB0_1053
	v_lshlrev_b32_e32 v4, 2, v168
	s_mov_b32 s0, 0x13800
	v_lshrrev_b32_e32 v3, 1, v168
	v_bfe_u32 v48, v168, 2, 6
	v_and_b32_e32 v12, 12, v4
	v_mad_u32_u24 v0, v46, s0, 16
	v_and_b32_e32 v10, 0x70, v3
	v_lshlrev_b32_e32 v5, 6, v48
	v_lshlrev_b32_e32 v6, 2, v12
	v_and_b32_e32 v2, 0xff, v168
	v_bfe_u32 v47, v168, 6, 2
	v_add3_u32 v50, v0, v5, v6
	v_mul_u32_u24_e32 v5, 0x90, v10
	v_and_b32_e32 v4, 0x7c, v4
	v_add3_u32 v14, v0, v5, v4
	v_lshl_add_u32 v52, v2, 2, v0
	v_lshlrev_b32_e32 v4, 2, v170
	v_cmp_lt_u32_e32 vcc, 63, v2
	v_mul_u32_u24_e32 v2, 0x90, v170
	v_lshlrev_b32_e32 v5, 5, v47
	v_and_b32_e32 v9, 15, v168
	v_and_b32_e32 v6, 24, v3
	v_and_b32_e32 v3, 48, v168
	s_waitcnt lgkmcnt(0)
	v_lshlrev_b32_e32 v1, 10, v168
	v_lshl_add_u32 v51, v47, 10, v0
	v_add_u32_e32 v53, v0, v4
	v_add3_u32 v54, v0, v2, v5
	v_add_u32_e32 v15, v0, v3
	v_mul_u32_u24_e32 v0, 0x48, v9
	v_and_b32_e32 v8, 0x7c00, v1
	v_mov_b32_e32 v1, 0
	v_or_b32_e32 v2, v5, v9
	v_lshl_add_u32 v55, v0, 1, v15
	s_lshl_b32 s18, s90, 1
	v_lshlrev_b32_e32 v0, 1, v170
	v_mul_u32_u24_e32 v16, 0x90, v2
	s_add_u32 s4, s68, 0xf1bd000
	v_lshl_add_u64 v[2:3], s[68:69], 0, v[0:1]
	s_mov_b64 s[0:1], 0xe13d000
	v_mov_b32_e32 v5, v1
	v_mov_b32_e32 v7, v1
	v_lshlrev_b32_e32 v0, 7, v9
	s_addc_u32 s5, s69, 0
	v_lshl_add_u64 v[2:3], v[2:3], 0, s[0:1]
	v_lshl_add_u64 v[4:5], s[68:69], 0, v[4:5]
	s_mov_b64 s[0:1], 0x51b5000
	v_lshl_add_u64 v[6:7], s[68:69], 0, v[6:7]
	v_lshl_or_b32 v0, v47, 12, v0
	s_add_u32 s6, s68, 0x133bd000
	v_lshl_add_u64 v[4:5], v[4:5], 0, s[0:1]
	v_lshl_add_u64 v[6:7], v[6:7], 0, v[0:1]
	s_mov_b64 s[0:1], 0x52bd000
	v_lshlrev_b32_e32 v49, 4, v47
	s_addc_u32 s7, s69, 0
	v_lshl_add_u64 v[6:7], v[6:7], 0, s[0:1]
	s_mov_b32 s19, 0x3e0f83e1
	s_movk_i32 s20, 0x84
	s_movk_i32 s21, 0xff00
	s_mov_b32 s22, 0x8000
	v_lshlrev_b32_e32 v8, 1, v8
	v_mov_b32_e32 v9, v1
	v_lshlrev_b32_e32 v10, 1, v10
	v_mov_b32_e32 v11, v1
	v_lshlrev_b32_e32 v12, 1, v12
	v_mov_b32_e32 v13, v1
	s_mov_b32 s23, 0xffff0000
	s_movk_i32 s24, 0x1000
	s_movk_i32 s25, 0x2000
	s_movk_i32 s26, 0x3000
	s_mov_b32 s27, 0xbfb8aa3b
	s_mov_b32 s28, 0x800000
	s_mov_b32 s29, 0x3f317217
	s_mov_b32 s30, 0x7f800000
	v_mov_b32_e32 v56, 0x41b17218
	s_mov_b32 s8, 0x3d800000
	v_add_u32_e32 v57, v15, v16
	v_add_u32_e32 v58, 0x3800, v14
	v_add_u32_e32 v59, 0x3c00, v14
	v_add_u32_e32 v60, 0x3e00, v14
	v_readfirstlane_b32 s98, v171
	s_nop 3
	s_cmp_lt_u32 s98, 4
	s_cbranch_scc1 .Lprio6_1
	s_setprio 1
.Lprio6_1:
	s_nop 0
	s_branch .LBB0_1017
.LBB0_1016:
	s_or_b64 exec, exec, s[0:1]
	s_waitcnt lgkmcnt(0)
	s_barrier
	ds_read_b128 v[16:19], v55 offset:5120
	ds_read_b128 v[20:23], v57 offset:14336
	ds_read_b128 v[24:27], v57 offset:14400
	ds_read_b128 v[28:31], v55 offset:5184
	ds_read_b128 v[36:39], v55 offset:7424
	ds_read_b128 v[40:43], v55 offset:7488
	ds_read_b128 v[66:69], v55 offset:9728
	ds_read_b128 v[70:73], v55 offset:9792
	ds_read_b128 v[78:81], v55 offset:12032
	ds_read_b128 v[82:85], v55 offset:12096
	s_waitcnt lgkmcnt(8)
	v_mfma_f32_16x16x32_bf16 v[32:35], v[16:19], v[20:23], 0
	ds_read_b128 v[86:89], v57 offset:16640
	v_lshlrev_b64 v[14:15], 14, v[14:15]
	v_lshl_add_u64 v[44:45], v[6:7], 0, v[14:15]
	s_waitcnt lgkmcnt(6)
	v_mfma_f32_16x16x32_bf16 v[62:65], v[36:39], v[20:23], 0
	s_add_i32 s9, s9, s18
	s_cmpk_lt_i32 s9, 0x1080
	s_waitcnt lgkmcnt(4)
	v_mfma_f32_16x16x32_bf16 v[74:77], v[66:69], v[20:23], 0
	s_waitcnt lgkmcnt(2)
	v_mfma_f32_16x16x32_bf16 v[20:23], v[78:81], v[20:23], 0
	v_mfma_f32_16x16x32_bf16 v[32:35], v[28:31], v[24:27], v[32:35]
	v_mfma_f32_16x16x32_bf16 v[62:65], v[40:43], v[24:27], v[62:65]
	v_mfma_f32_16x16x32_bf16 v[74:77], v[70:73], v[24:27], v[74:77]
	s_waitcnt lgkmcnt(1)
	v_mfma_f32_16x16x32_bf16 v[20:23], v[82:85], v[24:27], v[20:23]
	ds_read_b128 v[24:27], v57 offset:16704
	s_waitcnt lgkmcnt(1)
	v_mfma_f32_16x16x32_bf16 v[14:17], v[16:19], v[86:89], 0
	s_nop 0
	v_cvt_pk_bf16_f32 v18, v32, v33
	v_cvt_pk_bf16_f32 v19, v34, v35
	global_store_dwordx2 v[44:45], v[18:19], off
	s_waitcnt lgkmcnt(0)
	v_mfma_f32_16x16x32_bf16 v[14:17], v[28:31], v[24:27], v[14:17]
	v_cvt_pk_bf16_f32 v18, v62, v63
	v_cvt_pk_bf16_f32 v19, v64, v65
	global_store_dwordx2 v[44:45], v[18:19], off offset:32
	v_mfma_f32_16x16x32_bf16 v[32:35], v[36:39], v[86:89], 0
	v_cvt_pk_bf16_f32 v18, v74, v75
	s_nop 2
	v_cvt_pk_bf16_f32 v14, v14, v15
	v_cvt_pk_bf16_f32 v15, v16, v17
	global_store_dwordx2 v[44:45], v[14:15], off offset:2048
	v_mfma_f32_16x16x32_bf16 v[14:17], v[40:43], v[24:27], v[32:35]
	v_cvt_pk_bf16_f32 v19, v76, v77
	global_store_dwordx2 v[44:45], v[18:19], off offset:64
	v_cvt_pk_bf16_f32 v18, v20, v21
	v_mfma_f32_16x16x32_bf16 v[36:39], v[66:69], v[86:89], 0
	v_cvt_pk_bf16_f32 v19, v22, v23
	s_nop 2
	v_cvt_pk_bf16_f32 v14, v14, v15
	v_cvt_pk_bf16_f32 v15, v16, v17
	global_store_dwordx2 v[44:45], v[14:15], off offset:2080
	v_mfma_f32_16x16x32_bf16 v[14:17], v[70:73], v[24:27], v[36:39]
	global_store_dwordx2 v[44:45], v[18:19], off offset:96
	v_mfma_f32_16x16x32_bf16 v[62:65], v[78:81], v[86:89], 0
	s_nop 5
	v_cvt_pk_bf16_f32 v14, v14, v15
	v_cvt_pk_bf16_f32 v15, v16, v17
	global_store_dwordx2 v[44:45], v[14:15], off offset:2112
	v_mfma_f32_16x16x32_bf16 v[14:17], v[82:85], v[24:27], v[62:65]
	s_nop 7
	v_cvt_pk_bf16_f32 v14, v14, v15
	v_cvt_pk_bf16_f32 v15, v16, v17
	global_store_dwordx2 v[44:45], v[14:15], off offset:2144
	s_barrier
	s_cbranch_scc0 .LBB0_1053

; __device__ __forceinline__ void gla_a_item(const Params& P, int item, unsigned char* smem) {
;     float* sGLR = (float*)smem;
;     float* sPart = (float*)(smem + 4096);
;     bf16_t* sKDt = (bf16_t*)(smem + 5120);
;     bf16_t* sVt = (bf16_t*)(smem + 5120 + 9216);
;     const int n = item % 132, d = (item / 132) & 1, h = (item / 264) & 3, b = item / 1056;
;     const int rowbase = n < 4 ? NL + b * 256 + n * 64 : b * 8192 + (n - 4) * 64;
;     const bf16_t* Kb = (const bf16_t*)(P.ws + OFF_K); const bf16_t* V = (const bf16_t*)(P.ws + OFF_V); const bf16_t* GLR = (const bf16_t*)(P.ws + OFF_GLR);
;     const int tid = threadIdx.x & 255, lane = tid & 63, w = tid >> 6, dk = tid & 63, part = tid >> 6;
;     const VRegs vr = load_v_regs(V + (size_t)rowbase * 512 + h * 128, tid);
;     const f32x4 gl4 = load_bf4(GLR + (size_t)(rowbase + (tid >> 2)) * 32 + d * 16 + (tid & 3) * 4);
;     float kk[16];
; #pragma unroll
;     for (int ii = 0; ii < 16; ++ii) kk[ii] = bf2f(Kb[(size_t)(rowbase + part * 16 + ii) * 256 + h * 64 + dk]);
;     const GateW gw = load_gate_w(P, d, h, dk);
;     *(f32x4*)(sGLR + (tid >> 2) * 16 + (tid & 3) * 4) = gl4;
;     store_vt(vr, sVt, tid);
;     __syncthreads();
;     float pre[16];
;     const float tot = gate_prefix(gw, sGLR, 16, d, part, pre);
;     sPart[part * 64 + dk] = tot;
;     __syncthreads();
;     const float t0 = sPart[dk], t1 = sPart[64 + dk], t2 = sPart[128 + dk], t3 = sPart[192 + dk];
;     const float gtot = (t0 + t1) + (t2 + t3);
;     float off;
;     if (d == 0) off = part == 0 ? 0.f : (part == 1 ? t0 : (part == 2 ? t0 + t1 : t0 + t1 + t2));
;     else off = part == 3 ? 0.f : (part == 2 ? t3 : (part == 1 ? t3 + t2 : t3 + t2 + t1));
;     unsigned pk[8];
; #pragma unroll
;     for (int e = 0; e < 8; ++e) pk[e] = pk2(kk[2 * e] * __expf(gtot - (off + pre[2 * e])), kk[2 * e + 1] * __expf(gtot - (off + pre[2 * e + 1])));
;     *(uint4*)(sKDt + dk * LROW + part * 16) = make_uint4(pk[0], pk[1], pk[2], pk[3]);
; __device__ __forceinline__ void phase6(const Params& P, unsigned char* smem) {
;     ...
;     if (gridDim.x == 256) {
;         if (blockIdx.x < 160) { for (int base = blockIdx.x * 2; base < 2240; base += 320) gla_a_item(P, base + hb, smem + hb * HALF_LDS); }
;         else { for (int base = 2240 + ((int)blockIdx.x - 160) * 2; base < 4224; base += 192) gla_a_item(P, base + hb, smem + hb * HALF_LDS); }
.LBB0_1054:
	s_andn2_b64 vcc, exec, s[0:1]
	s_cbranch_vccnz .LBB0_1135
	s_lshl_b32 s9, s33, 1
	s_cmpk_gt_u32 s33, 0x9f
	s_mov_b64 s[0:1], -1
	s_cbranch_scc0 .LBB0_1096
	s_add_i32 s0, s9, 0x780
	s_cmpk_gt_i32 s0, 0x107f
	s_cbranch_scc1 .LBB0_1095
	v_lshlrev_b32_e32 v4, 2, v168
	s_mov_b32 s0, 0x13800
	v_lshrrev_b32_e32 v3, 1, v168
	v_bfe_u32 v48, v168, 2, 6
	v_and_b32_e32 v12, 12, v4
	v_mad_u32_u24 v0, v46, s0, 16
	v_and_b32_e32 v10, 0x70, v3
	v_lshlrev_b32_e32 v5, 6, v48
	v_lshlrev_b32_e32 v6, 2, v12
	v_and_b32_e32 v2, 0xff, v168
	v_bfe_u32 v47, v168, 6, 2
	v_add3_u32 v50, v0, v5, v6
	v_mul_u32_u24_e32 v5, 0x90, v10
	v_and_b32_e32 v4, 0x7c, v4
	v_add3_u32 v14, v0, v5, v4
	v_lshl_add_u32 v52, v2, 2, v0
	v_lshlrev_b32_e32 v4, 2, v170
	v_cmp_lt_u32_e32 vcc, 63, v2
	v_mul_u32_u24_e32 v2, 0x90, v170
	v_lshlrev_b32_e32 v5, 5, v47
	v_and_b32_e32 v9, 15, v168
	v_and_b32_e32 v6, 24, v3
	v_and_b32_e32 v3, 48, v168
	s_waitcnt lgkmcnt(0)
	v_lshlrev_b32_e32 v1, 10, v168
	v_lshl_add_u32 v51, v47, 10, v0
	v_add_u32_e32 v53, v0, v4
	v_add3_u32 v54, v0, v2, v5
	v_add_u32_e32 v15, v0, v3
	v_mul_u32_u24_e32 v0, 0x48, v9
	v_and_b32_e32 v8, 0x7c00, v1
	v_mov_b32_e32 v1, 0
	v_or_b32_e32 v2, v5, v9
	v_lshl_add_u32 v55, v0, 1, v15
	v_lshlrev_b32_e32 v0, 1, v170
	v_mul_u32_u24_e32 v16, 0x90, v2
	s_add_u32 s4, s68, 0xf1bd000
	v_lshl_add_u64 v[2:3], s[68:69], 0, v[0:1]
	s_mov_b64 s[0:1], 0xe13d000
	v_mov_b32_e32 v5, v1
	v_mov_b32_e32 v7, v1
	v_lshlrev_b32_e32 v0, 7, v9
	s_addc_u32 s5, s69, 0
	v_lshl_add_u64 v[2:3], v[2:3], 0, s[0:1]
	v_lshl_add_u64 v[4:5], s[68:69], 0, v[4:5]
	s_mov_b64 s[0:1], 0x51b5000
	v_lshl_add_u64 v[6:7], s[68:69], 0, v[6:7]
	v_lshl_or_b32 v0, v47, 12, v0
	s_add_u32 s6, s68, 0x133bd000
	v_lshl_add_u64 v[4:5], v[4:5], 0, s[0:1]
	v_lshl_add_u64 v[6:7], v[6:7], 0, v[0:1]
	s_mov_b64 s[0:1], 0x52bd000
	v_lshlrev_b32_e32 v49, 4, v47
	s_addc_u32 s7, s69, 0
	v_lshl_add_u64 v[6:7], v[6:7], 0, s[0:1]
	s_add_i32 s18, s9, 0x6c0
	s_mov_b32 s19, 0x3e0f83e1
	s_movk_i32 s20, 0x84
	s_movk_i32 s21, 0xff00
	s_mov_b32 s22, 0x8000
	v_lshlrev_b32_e32 v8, 1, v8
	v_mov_b32_e32 v9, v1
	v_lshlrev_b32_e32 v10, 1, v10
	v_mov_b32_e32 v11, v1
	v_lshlrev_b32_e32 v12, 1, v12
	v_mov_b32_e32 v13, v1
	s_mov_b32 s23, 0xffff0000
	s_movk_i32 s24, 0x1000
	s_movk_i32 s25, 0x2000
	s_movk_i32 s26, 0x3000
	s_mov_b32 s27, 0xbfb8aa3b
	s_mov_b32 s28, 0x800000
	s_mov_b32 s29, 0x3f317217
	s_mov_b32 s30, 0x7f800000
	v_mov_b32_e32 v56, 0x41b17218
	s_mov_b32 s8, 0x3d800000
	v_add_u32_e32 v57, v15, v16
	v_add_u32_e32 v58, 0x3800, v14
	v_add_u32_e32 v59, 0x3c00, v14
	v_add_u32_e32 v60, 0x3e00, v14
	v_readfirstlane_b32 s98, v171
	s_nop 3
	s_cmp_lt_u32 s98, 4
	s_cbranch_scc1 .Lprio6_2
	s_setprio 1
.Lprio6_2:
	s_nop 0
	s_branch .LBB0_1059
.LBB0_1058:
	s_or_b64 exec, exec, s[0:1]
	s_waitcnt lgkmcnt(0)
	s_barrier
	ds_read_b128 v[16:19], v55 offset:5120
	ds_read_b128 v[20:23], v57 offset:14336
	ds_read_b128 v[24:27], v57 offset:14400
	ds_read_b128 v[28:31], v55 offset:5184
	ds_read_b128 v[36:39], v55 offset:7424
	ds_read_b128 v[40:43], v55 offset:7488
	ds_read_b128 v[66:69], v55 offset:9728
	ds_read_b128 v[70:73], v55 offset:9792
	ds_read_b128 v[78:81], v55 offset:12032
	ds_read_b128 v[82:85], v55 offset:12096
	s_waitcnt lgkmcnt(8)
	v_mfma_f32_16x16x32_bf16 v[32:35], v[16:19], v[20:23], 0
	ds_read_b128 v[86:89], v57 offset:16640
	v_lshlrev_b64 v[14:15], 14, v[14:15]
	v_lshl_add_u64 v[44:45], v[6:7], 0, v[14:15]
	s_waitcnt lgkmcnt(6)
	v_mfma_f32_16x16x32_bf16 v[62:65], v[36:39], v[20:23], 0
	s_addk_i32 s18, 0xc0
	s_cmpk_gt_i32 s18, 0xfbf
	s_waitcnt lgkmcnt(4)
	v_mfma_f32_16x16x32_bf16 v[74:77], v[66:69], v[20:23], 0
	s_waitcnt lgkmcnt(2)
	v_mfma_f32_16x16x32_bf16 v[20:23], v[78:81], v[20:23], 0
	v_mfma_f32_16x16x32_bf16 v[32:35], v[28:31], v[24:27], v[32:35]
	v_mfma_f32_16x16x32_bf16 v[62:65], v[40:43], v[24:27], v[62:65]
	v_mfma_f32_16x16x32_bf16 v[74:77], v[70:73], v[24:27], v[74:77]
	s_waitcnt lgkmcnt(1)
	v_mfma_f32_16x16x32_bf16 v[20:23], v[82:85], v[24:27], v[20:23]
	ds_read_b128 v[24:27], v57 offset:16704
	s_waitcnt lgkmcnt(1)
	v_mfma_f32_16x16x32_bf16 v[14:17], v[16:19], v[86:89], 0
	s_nop 0
	v_cvt_pk_bf16_f32 v18, v32, v33
	v_cvt_pk_bf16_f32 v19, v34, v35
	global_store_dwordx2 v[44:45], v[18:19], off
	s_waitcnt lgkmcnt(0)
	v_mfma_f32_16x16x32_bf16 v[14:17], v[28:31], v[24:27], v[14:17]
	v_cvt_pk_bf16_f32 v18, v62, v63
	v_cvt_pk_bf16_f32 v19, v64, v65
	global_store_dwordx2 v[44:45], v[18:19], off offset:32
	v_mfma_f32_16x16x32_bf16 v[32:35], v[36:39], v[86:89], 0
	v_cvt_pk_bf16_f32 v18, v74, v75
	s_nop 2
	v_cvt_pk_bf16_f32 v14, v14, v15
	v_cvt_pk_bf16_f32 v15, v16, v17
	global_store_dwordx2 v[44:45], v[14:15], off offset:2048
	v_mfma_f32_16x16x32_bf16 v[14:17], v[40:43], v[24:27], v[32:35]
	v_cvt_pk_bf16_f32 v19, v76, v77
	global_store_dwordx2 v[44:45], v[18:19], off offset:64
	v_cvt_pk_bf16_f32 v18, v20, v21
	v_mfma_f32_16x16x32_bf16 v[36:39], v[66:69], v[86:89], 0
	v_cvt_pk_bf16_f32 v19, v22, v23
	s_nop 2
	v_cvt_pk_bf16_f32 v14, v14, v15
	v_cvt_pk_bf16_f32 v15, v16, v17
	global_store_dwordx2 v[44:45], v[14:15], off offset:2080
	v_mfma_f32_16x16x32_bf16 v[14:17], v[70:73], v[24:27], v[36:39]
	global_store_dwordx2 v[44:45], v[18:19], off offset:96
	v_mfma_f32_16x16x32_bf16 v[62:65], v[78:81], v[86:89], 0
	s_nop 5
	v_cvt_pk_bf16_f32 v14, v14, v15
	v_cvt_pk_bf16_f32 v15, v16, v17
	global_store_dwordx2 v[44:45], v[14:15], off offset:2112
	v_mfma_f32_16x16x32_bf16 v[14:17], v[82:85], v[24:27], v[62:65]
	s_nop 7
	v_cvt_pk_bf16_f32 v14, v14, v15
	v_cvt_pk_bf16_f32 v15, v16, v17
	global_store_dwordx2 v[44:45], v[14:15], off offset:2144
	s_barrier
	s_cbranch_scc1 .LBB0_1095

; __device__ __forceinline__ void gla_a_item(const Params& P, int item, unsigned char* smem) {
;     float* sGLR = (float*)smem;
;     float* sPart = (float*)(smem + 4096);
;     bf16_t* sKDt = (bf16_t*)(smem + 5120);
;     bf16_t* sVt = (bf16_t*)(smem + 5120 + 9216);
;     const int n = item % 132, d = (item / 132) & 1, h = (item / 264) & 3, b = item / 1056;
;     const int rowbase = n < 4 ? NL + b * 256 + n * 64 : b * 8192 + (n - 4) * 64;
;     const bf16_t* Kb = (const bf16_t*)(P.ws + OFF_K); const bf16_t* V = (const bf16_t*)(P.ws + OFF_V); const bf16_t* GLR = (const bf16_t*)(P.ws + OFF_GLR);
;     const int tid = threadIdx.x & 255, lane = tid & 63, w = tid >> 6, dk = tid & 63, part = tid >> 6;
;     const VRegs vr = load_v_regs(V + (size_t)rowbase * 512 + h * 128, tid);
;     const f32x4 gl4 = load_bf4(GLR + (size_t)(rowbase + (tid >> 2)) * 32 + d * 16 + (tid & 3) * 4);
;     float kk[16];
; #pragma unroll
;     for (int ii = 0; ii < 16; ++ii) kk[ii] = bf2f(Kb[(size_t)(rowbase + part * 16 + ii) * 256 + h * 64 + dk]);
;     const GateW gw = load_gate_w(P, d, h, dk);
;     *(f32x4*)(sGLR + (tid >> 2) * 16 + (tid & 3) * 4) = gl4;
;     store_vt(vr, sVt, tid);
;     __syncthreads();
;     float pre[16];
;     const float tot = gate_prefix(gw, sGLR, 16, d, part, pre);
;     sPart[part * 64 + dk] = tot;
;     __syncthreads();
;     const float t0 = sPart[dk], t1 = sPart[64 + dk], t2 = sPart[128 + dk], t3 = sPart[192 + dk];
;     const float gtot = (t0 + t1) + (t2 + t3);
;     float off;
;     if (d == 0) off = part == 0 ? 0.f : (part == 1 ? t0 : (part == 2 ? t0 + t1 : t0 + t1 + t2));
;     else off = part == 3 ? 0.f : (part == 2 ? t3 : (part == 1 ? t3 + t2 : t3 + t2 + t1));
;     unsigned pk[8];
; #pragma unroll
;     for (int e = 0; e < 8; ++e) pk[e] = pk2(kk[2 * e] * __expf(gtot - (off + pre[2 * e])), kk[2 * e + 1] * __expf(gtot - (off + pre[2 * e + 1])));
;     *(uint4*)(sKDt + dk * LROW + part * 16) = make_uint4(pk[0], pk[1], pk[2], pk[3]);
;     *(uint4*)(sKDt + dk * LROW + part * 16 + 8) = make_uint4(pk[4], pk[5], pk[6], pk[7]);
; __device__ __forceinline__ void phase6(const Params& P, unsigned char* smem) {
;     ...
;     if (gridDim.x == 256) {
;         if (blockIdx.x < 160) { for (int base = blockIdx.x * 2; base < 2240; base += 320) gla_a_item(P, base + hb, smem + hb * HALF_LDS); }
.LBB0_1096:
	s_andn2_b64 vcc, exec, s[0:1]
	s_cbranch_vccnz .LBB0_1135
	v_lshlrev_b32_e32 v4, 2, v168
	s_mov_b32 s0, 0x13800
	v_lshrrev_b32_e32 v3, 1, v168
	v_bfe_u32 v45, v168, 2, 6
	v_and_b32_e32 v12, 12, v4
	v_mad_u32_u24 v0, v46, s0, 16
	v_and_b32_e32 v10, 0x70, v3
	v_lshlrev_b32_e32 v5, 6, v45
	v_lshlrev_b32_e32 v6, 2, v12
	v_and_b32_e32 v2, 0xff, v168
	v_bfe_u32 v44, v168, 6, 2
	v_add3_u32 v48, v0, v5, v6
	v_mul_u32_u24_e32 v5, 0x90, v10
	v_and_b32_e32 v4, 0x7c, v4
	v_add3_u32 v14, v0, v5, v4
	v_lshl_add_u32 v50, v2, 2, v0
	v_lshlrev_b32_e32 v4, 2, v170
	v_cmp_lt_u32_e32 vcc, 63, v2
	v_mul_u32_u24_e32 v2, 0x90, v170
	v_lshlrev_b32_e32 v5, 5, v44
	v_and_b32_e32 v9, 15, v168
	v_and_b32_e32 v6, 24, v3
	v_and_b32_e32 v3, 48, v168
	s_waitcnt lgkmcnt(0)
	v_lshlrev_b32_e32 v1, 10, v168
	v_lshl_add_u32 v49, v44, 10, v0
	v_add_u32_e32 v51, v0, v4
	v_add3_u32 v52, v0, v2, v5
	v_add_u32_e32 v15, v0, v3
	v_mul_u32_u24_e32 v0, 0x48, v9
	v_and_b32_e32 v8, 0x7c00, v1
	v_mov_b32_e32 v1, 0
	v_or_b32_e32 v2, v5, v9
	v_lshl_add_u32 v53, v0, 1, v15
	v_lshlrev_b32_e32 v0, 1, v170
	v_mul_u32_u24_e32 v16, 0x90, v2
	s_add_u32 s4, s68, 0xf1bd000
	v_lshl_add_u64 v[2:3], s[68:69], 0, v[0:1]
	s_mov_b64 s[0:1], 0xe13d000
	v_mov_b32_e32 v5, v1
	v_mov_b32_e32 v7, v1
	v_lshlrev_b32_e32 v0, 7, v9
	s_addc_u32 s5, s69, 0
	v_lshl_add_u64 v[2:3], v[2:3], 0, s[0:1]
	v_lshl_add_u64 v[4:5], s[68:69], 0, v[4:5]
	s_mov_b64 s[0:1], 0x51b5000
	v_lshl_add_u64 v[6:7], s[68:69], 0, v[6:7]
	v_lshl_or_b32 v0, v44, 12, v0
	s_add_u32 s6, s68, 0x133bd000
	v_lshl_add_u64 v[4:5], v[4:5], 0, s[0:1]
	v_lshl_add_u64 v[6:7], v[6:7], 0, v[0:1]
	s_mov_b64 s[0:1], 0x52bd000
	v_lshlrev_b32_e32 v47, 4, v44
	s_addc_u32 s7, s69, 0
	v_lshl_add_u64 v[6:7], v[6:7], 0, s[0:1]
	s_mov_b32 s18, 0x3e0f83e1
	s_movk_i32 s19, 0x84
	s_movk_i32 s20, 0xff00
	s_mov_b32 s21, 0x8000
	v_lshlrev_b32_e32 v8, 1, v8
	v_mov_b32_e32 v9, v1
	v_lshlrev_b32_e32 v10, 1, v10
	v_mov_b32_e32 v11, v1
	v_lshlrev_b32_e32 v12, 1, v12
	v_mov_b32_e32 v13, v1
	s_mov_b32 s22, 0xffff0000
	s_movk_i32 s23, 0x1000
	s_movk_i32 s24, 0x2000
	s_movk_i32 s25, 0x3000
	s_mov_b32 s26, 0xbfb8aa3b
	s_mov_b32 s27, 0x800000
	s_mov_b32 s28, 0x3f317217
	s_mov_b32 s29, 0x7f800000
	v_mov_b32_e32 v54, 0x41b17218
	s_mov_b32 s8, 0x3d800000
	v_add_u32_e32 v55, v15, v16
	v_add_u32_e32 v56, 0x3800, v14
	v_add_u32_e32 v57, 0x3c00, v14
	v_add_u32_e32 v58, 0x3e00, v14
	v_readfirstlane_b32 s98, v171
	s_nop 3
	s_cmp_lt_u32 s98, 4
	s_cbranch_scc1 .Lprio6_3
	s_setprio 1
.Lprio6_3:
	s_nop 0
	s_branch .LBB0_1099
.LBB0_1098:
	s_or_b64 exec, exec, s[0:1]
	s_waitcnt lgkmcnt(0)
	s_barrier
	ds_read_b128 v[14:17], v53 offset:5120
	ds_read_b128 v[18:21], v55 offset:14336
	ds_read_b128 v[22:25], v55 offset:14400
	ds_read_b128 v[26:29], v53 offset:5184
	ds_read_b128 v[34:37], v53 offset:7424
	ds_read_b128 v[38:41], v53 offset:7488
	ds_read_b128 v[64:67], v53 offset:9728
	ds_read_b128 v[68:71], v53 offset:9792
	ds_read_b128 v[76:79], v53 offset:12032
	ds_read_b128 v[80:83], v53 offset:12096
	s_waitcnt lgkmcnt(8)
	v_mfma_f32_16x16x32_bf16 v[30:33], v[14:17], v[18:21], 0
	ds_read_b128 v[84:87], v55 offset:16640
	s_add_i32 s0, s9, 0x140
	s_cmpk_gt_u32 s9, 0x77f
	s_waitcnt lgkmcnt(6)
	v_mfma_f32_16x16x32_bf16 v[60:63], v[34:37], v[18:21], 0
	s_mov_b32 s9, s0
	s_waitcnt lgkmcnt(4)
	v_mfma_f32_16x16x32_bf16 v[72:75], v[64:67], v[18:21], 0
	s_waitcnt lgkmcnt(2)
	v_mfma_f32_16x16x32_bf16 v[18:21], v[76:79], v[18:21], 0
	v_mfma_f32_16x16x32_bf16 v[30:33], v[26:29], v[22:25], v[30:33]
	v_mfma_f32_16x16x32_bf16 v[60:63], v[38:41], v[22:25], v[60:63]
	v_mfma_f32_16x16x32_bf16 v[72:75], v[68:71], v[22:25], v[72:75]
	s_nop 5
	v_cvt_pk_bf16_f32 v30, v30, v31
	v_cvt_pk_bf16_f32 v31, v32, v33
	s_waitcnt lgkmcnt(1)
	v_mfma_f32_16x16x32_bf16 v[18:21], v[80:83], v[22:25], v[18:21]
	v_lshlrev_b64 v[22:23], 14, v[0:1]
	v_lshl_add_u64 v[42:43], v[6:7], 0, v[22:23]
	ds_read_b128 v[22:25], v55 offset:16704
	s_waitcnt lgkmcnt(1)
	v_mfma_f32_16x16x32_bf16 v[14:17], v[14:17], v[84:87], 0
	global_store_dwordx2 v[42:43], v[30:31], off
	s_nop 1
	v_cvt_pk_bf16_f32 v18, v18, v19
	v_cvt_pk_bf16_f32 v19, v20, v21
	s_waitcnt lgkmcnt(0)
	v_mfma_f32_16x16x32_bf16 v[14:17], v[26:29], v[22:25], v[14:17]
	global_store_dwordx2 v[42:43], v[18:19], off offset:96
	v_mfma_f32_16x16x32_bf16 v[30:33], v[34:37], v[84:87], 0
	v_cvt_pk_bf16_f32 v34, v60, v61
	s_nop 4
	v_cvt_pk_bf16_f32 v14, v14, v15
	v_cvt_pk_bf16_f32 v15, v16, v17
	v_cvt_pk_bf16_f32 v35, v62, v63
	global_store_dwordx2 v[42:43], v[14:15], off offset:2048
	v_mfma_f32_16x16x32_bf16 v[14:17], v[38:41], v[22:25], v[30:33]
	global_store_dwordx2 v[42:43], v[34:35], off offset:32
	v_cvt_pk_bf16_f32 v60, v72, v73
	v_cvt_pk_bf16_f32 v61, v74, v75
	v_mfma_f32_16x16x32_bf16 v[34:37], v[64:67], v[84:87], 0
	global_store_dwordx2 v[42:43], v[60:61], off offset:64
	s_nop 2
	v_cvt_pk_bf16_f32 v14, v14, v15
	v_cvt_pk_bf16_f32 v15, v16, v17
	global_store_dwordx2 v[42:43], v[14:15], off offset:2080
	v_mfma_f32_16x16x32_bf16 v[14:17], v[68:71], v[22:25], v[34:37]
	v_mfma_f32_16x16x32_bf16 v[60:63], v[76:79], v[84:87], 0
	s_nop 6
	v_cvt_pk_bf16_f32 v14, v14, v15
	v_cvt_pk_bf16_f32 v15, v16, v17
	global_store_dwordx2 v[42:43], v[14:15], off offset:2112
	v_mfma_f32_16x16x32_bf16 v[14:17], v[80:83], v[22:25], v[60:63]
	s_nop 7
	v_cvt_pk_bf16_f32 v14, v14, v15
	v_cvt_pk_bf16_f32 v15, v16, v17
	global_store_dwordx2 v[42:43], v[14:15], off offset:2144
	s_barrier
	s_cbranch_scc1 .LBB0_1135

; #define PG8_LAS __attribute__((address_space(3)))
; __device__ __forceinline__ void phase6(const Params& P, unsigned char* smem) {
;     ...
;     for (int base = blockIdx.x * 2; base < 4224; base += gridDim.x * 2) gla_a_item(P, base + hb, smem + hb * HALF_LDS);
;     GemmD g{}; g.A = (const bf16_t*)(P.ws + OFF_U); g.Bt = (const bf16_t*)(P.ws + OFF_WE); g.lda = 768; g.ldb = 512; g.K = 512; g.nM = 5; g.nN = 1; g.nG = 32;
;     g.gsA = (size_t)UROWS * 768; g.gsB = (size_t)256 * 512;
;     EpiE E; E.E = (float*)(P.ws + OFF_E);
;     pg8::gemm_phase((PG8_LAS unsigned char*)smem, g, E);
.LBB0_1135:
	s_setprio 0
	s_nop 0
	s_nop 0
	s_nop 0
	s_nop 0
	s_nop 0
	s_nop 0
	s_nop 0
	s_nop 0
	s_nop 0
	s_nop 0
	s_nop 0
	s_nop 0
	s_nop 0
	s_cmpk_lt_u32 s33, 0xa0
	s_cselect_b64 s[0:1], -1, 0
	s_cmpk_gt_u32 s33, 0x9f
	v_readfirstlane_b32 s24, v168
	s_cbranch_scc0 .LBB0_1138
	s_andn2_b64 vcc, exec, s[0:1]
	s_cbranch_vccz .LBB0_1139
